# more read-once / write-once streams use the non-temporal hint: chunk increments in the scans, f32 inputs in the prologue, residual stream and y in the final norm
# speedup vs baseline: 1.0099x; 1.0079x over previous
.LBB0_45:
	s_or_b64 exec, exec, s[2:3]
	v_lshlrev_b32_e32 v42, 4, v38
	v_lshl_add_u64 v[10:11], v[6:7], 0, v[42:43]
	global_load_dwordx4 v[30:33], v[10:11], off nt
	global_load_dwordx4 v[22:25], v[10:11], off offset:1024 nt
	global_load_dwordx4 v[14:17], v[10:11], off offset:2048 nt
	global_load_dwordx4 v[6:9], v[10:11], off offset:3072 nt
	v_add_u32_e32 v10, s42, v40
	v_cmp_gt_i32_e64 s[2:3], s0, v10
	s_nop 1
	v_cndmask_b32_e64 v12, v40, v10, s[2:3]
	v_cmp_lt_i32_e64 s[4:5], s1, v12
	s_and_saveexec_b64 s[30:31], s[4:5]
	s_xor_b64 s[30:31], exec, s[30:31]
	s_cbranch_execz .LBB0_51
	v_cmp_lt_u32_e64 s[4:5], s33, v12
	s_and_saveexec_b64 s[38:39], s[4:5]
	s_xor_b64 s[4:5], exec, s[38:39]
	s_cbranch_execz .LBB0_48
	s_load_dwordx2 s[38:39], s[12:13], 0x48
	v_add_u32_e32 v12, 0xffffbc00, v12
	v_mov_b32_e32 v13, v43
	v_lshlrev_b64 v[4:5], 12, v[12:13]
	v_lshlrev_b64 v[18:19], 11, v[12:13]
	s_waitcnt lgkmcnt(0)
	v_lshl_add_u64 v[10:11], s[38:39], 0, v[4:5]
	v_lshl_add_u64 v[4:5], s[22:23], 0, v[18:19]
	v_lshl_add_u64 v[48:49], v[12:13], 3, s[18:19]

.LBB0_53:
	s_or_b64 exec, exec, s[4:5]
	v_lshl_add_u64 v[52:53], v[10:11], 0, v[42:43]
	global_load_dwordx4 v[34:37], v[52:53], off nt
	global_load_dwordx4 v[26:29], v[52:53], off offset:1024 nt
	global_load_dwordx4 v[18:21], v[52:53], off offset:2048 nt
	global_load_dwordx4 v[10:13], v[52:53], off offset:3072 nt
	s_waitcnt vmcnt(0)
	v_mul_f32_e32 v39, v31, v31
	v_mul_f32_e32 v41, v33, v33
	v_fmac_f32_e32 v39, v30, v30
	v_fmac_f32_e32 v41, v32, v32
	v_add_f32_e32 v39, v39, v41
	s_waitcnt vmcnt(6)
	v_mul_f32_e32 v41, v23, v23
	v_mul_f32_e32 v42, v25, v25
	v_fmac_f32_e32 v41, v22, v22
	v_fmac_f32_e32 v42, v24, v24
	v_add_f32_e32 v41, v41, v42
	v_add_f32_e32 v39, v39, v41
	s_waitcnt vmcnt(5)
	v_mul_f32_e32 v41, v15, v15
	v_mul_f32_e32 v42, v17, v17
	v_fmac_f32_e32 v41, v14, v14
	v_fmac_f32_e32 v42, v16, v16
	v_add_f32_e32 v41, v41, v42
	v_add_f32_e32 v39, v39, v41
	s_waitcnt vmcnt(4)
	v_mul_f32_e32 v41, v7, v7
	v_mul_f32_e32 v42, v9, v9
	v_fmac_f32_e32 v41, v6, v6
	v_fmac_f32_e32 v42, v8, v8
	v_add_f32_e32 v41, v41, v42
	v_add_f32_e32 v39, v39, v41
	v_lshlrev_b32_e32 v42, 3, v38
	v_lshl_add_u64 v[2:3], v[2:3], 0, v[42:43]
	v_add_f32_dpp v39, v39, v39 quad_perm:[1,0,3,2] row_mask:0xf bank_mask:0xf bound_ctrl:1
	s_nop 1
	v_add_f32_dpp v39, v39, v39 quad_perm:[2,3,0,1] row_mask:0xf bank_mask:0xf bound_ctrl:1
	s_nop 1
	v_add_f32_dpp v39, v39, v39 row_half_mirror row_mask:0xf bank_mask:0xf bound_ctrl:1
	s_nop 1
	v_add_f32_dpp v39, v39, v39 row_mirror row_mask:0xf bank_mask:0xf bound_ctrl:1
	s_nop 0
	v_readlane_b32 s4, v39, 0
	v_readlane_b32 s37, v39, 16
	v_readlane_b32 s5, v39, 32
	v_readlane_b32 s38, v39, 48
	v_bfe_u32 v39, v30, 16, 1
	v_add3_u32 v30, v30, v39, s34
	v_bfe_u32 v39, v31, 16, 1
	v_lshrrev_b32_e32 v30, 16, v30
	v_add3_u32 v31, v31, v39, s34
	v_and_or_b32 v30, v31, s35, v30
	v_bfe_u32 v31, v32, 16, 1
	v_add3_u32 v31, v32, v31, s34
	v_bfe_u32 v32, v33, 16, 1
	v_lshrrev_b32_e32 v31, 16, v31
	v_add3_u32 v32, v33, v32, s34
	v_and_or_b32 v31, v32, s35, v31
	flat_store_dwordx2 v[2:3], v[30:31]
	v_bfe_u32 v30, v22, 16, 1
	v_add3_u32 v22, v22, v30, s34
	v_bfe_u32 v30, v23, 16, 1
	v_lshrrev_b32_e32 v22, 16, v22
	v_add3_u32 v23, v23, v30, s34
	v_and_or_b32 v22, v23, s35, v22
	v_bfe_u32 v23, v24, 16, 1
	v_add3_u32 v23, v24, v23, s34
	v_bfe_u32 v24, v25, 16, 1
	v_lshrrev_b32_e32 v23, 16, v23
	v_add3_u32 v24, v25, v24, s34
	v_and_or_b32 v23, v24, s35, v23
	flat_store_dwordx2 v[2:3], v[22:23] offset:512
	v_bfe_u32 v22, v14, 16, 1
	v_add3_u32 v14, v14, v22, s34
	v_bfe_u32 v22, v15, 16, 1
	v_lshrrev_b32_e32 v14, 16, v14
	v_add3_u32 v15, v15, v22, s34
	v_and_or_b32 v14, v15, s35, v14
	v_bfe_u32 v15, v16, 16, 1
	v_add3_u32 v15, v16, v15, s34
	v_bfe_u32 v16, v17, 16, 1
	v_lshrrev_b32_e32 v15, 16, v15
	v_add3_u32 v16, v17, v16, s34
	v_and_or_b32 v15, v16, s35, v15
	flat_store_dwordx2 v[2:3], v[14:15] offset:1024
	v_bfe_u32 v14, v6, 16, 1
	v_add3_u32 v6, v6, v14, s34
	v_bfe_u32 v14, v7, 16, 1
	v_lshrrev_b32_e32 v6, 16, v6
	v_add3_u32 v7, v7, v14, s34
	v_and_or_b32 v6, v7, s35, v6
	v_bfe_u32 v7, v8, 16, 1
	v_add3_u32 v7, v8, v7, s34
	v_bfe_u32 v8, v9, 16, 1
	v_lshrrev_b32_e32 v7, 16, v7
	v_add3_u32 v8, v9, v8, s34
	v_and_or_b32 v7, v8, s35, v7
	flat_store_dwordx2 v[2:3], v[6:7] offset:1536
	s_and_saveexec_b64 s[30:31], vcc
	s_cbranch_execz .LBB0_55
	v_mov_b32_e32 v2, s37
	v_mov_b32_e32 v3, s38
	v_pk_add_f32 v[2:3], s[4:5], v[2:3]
	s_nop 0
	v_add_f32_e32 v2, v2, v3
	v_mul_f32_e32 v2, 0x4b800000, v2
	v_trunc_f32_e32 v2, v2
	v_mul_f32_e32 v3, 0x2f800000, v2
	v_floor_f32_e32 v3, v3
	v_fmac_f32_e32 v2, 0xcf800000, v3
	v_cvt_u32_f32_e32 v2, v2
	v_cvt_u32_f32_e32 v3, v3
	global_store_dwordx2 v[50:51], v[2:3], off

.LBB0_314:
	s_lshl_b64 s[14:15], s[30:31], 1
	v_lshl_add_u64 v[16:17], v[8:9], 0, s[14:15]
	global_load_dwordx2 v[16:17], v[16:17], off nt
	s_or_b32 s16, s30, 0x4000
	s_mov_b32 s17, s31
	s_or_b32 s18, s30, 0x8000
	s_mov_b32 s19, s31
	s_or_b32 s20, s30, 0xc000
	s_mov_b32 s21, s31
	s_or_b32 s22, s30, 0x10000
	s_mov_b32 s23, s31
	s_or_b32 s24, s30, 0x14000
	s_mov_b32 s25, s31
	s_or_b32 s26, s30, 0x18000
	s_mov_b32 s27, s31
	s_or_b32 s36, s30, 0x1c000
	s_mov_b32 s37, s31
	s_or_b32 s38, s30, 0x20000
	s_mov_b32 s39, s31
	s_or_b32 s40, s30, 0x24000
	s_mov_b32 s41, s31
	s_or_b32 s42, s30, 0x28000
	s_mov_b32 s43, s31
	s_or_b32 s46, s30, 0x2c000
	s_mov_b32 s47, s31
	s_or_b32 s50, s30, 0x30000
	s_mov_b32 s51, s31
	s_or_b32 s56, s30, 0x34000
	s_mov_b32 s57, s31
	s_or_b32 s62, s30, 0x38000
	s_mov_b32 s63, s31
	s_or_b32 s30, s30, 0x3c000
	s_lshl_b64 s[0:1], s[16:17], 1
	s_lshl_b64 s[16:17], s[18:19], 1
	s_lshl_b64 s[18:19], s[20:21], 1
	s_lshl_b64 s[20:21], s[22:23], 1
	s_lshl_b64 s[22:23], s[24:25], 1
	s_lshl_b64 s[24:25], s[26:27], 1
	s_lshl_b64 s[26:27], s[36:37], 1
	s_lshl_b64 s[34:35], s[38:39], 1
	s_lshl_b64 s[36:37], s[40:41], 1
	s_lshl_b64 s[38:39], s[42:43], 1
	s_lshl_b64 s[40:41], s[46:47], 1
	s_lshl_b64 s[42:43], s[50:51], 1
	s_lshl_b64 s[44:45], s[56:57], 1
	s_lshl_b64 s[46:47], s[62:63], 1
	s_lshl_b64 s[48:49], s[30:31], 1
	v_lshl_add_u64 v[20:21], v[8:9], 0, s[0:1]
	v_lshl_add_u64 v[22:23], v[8:9], 0, s[16:17]
	v_lshl_add_u64 v[24:25], v[8:9], 0, s[18:19]
	v_lshl_add_u64 v[26:27], v[8:9], 0, s[20:21]
	v_lshl_add_u64 v[28:29], v[8:9], 0, s[22:23]
	v_lshl_add_u64 v[30:31], v[8:9], 0, s[24:25]
	v_lshl_add_u64 v[32:33], v[8:9], 0, s[26:27]
	v_lshl_add_u64 v[34:35], v[8:9], 0, s[34:35]
	v_lshl_add_u64 v[36:37], v[8:9], 0, s[36:37]
	v_lshl_add_u64 v[38:39], v[8:9], 0, s[38:39]
	v_lshl_add_u64 v[40:41], v[8:9], 0, s[40:41]
	v_lshl_add_u64 v[42:43], v[8:9], 0, s[42:43]
	v_lshl_add_u64 v[44:45], v[8:9], 0, s[44:45]
	v_lshl_add_u64 v[46:47], v[8:9], 0, s[46:47]
	v_lshl_add_u64 v[48:49], v[8:9], 0, s[48:49]
	global_load_dwordx2 v[20:21], v[20:21], off nt
	s_nop 0
	global_load_dwordx2 v[22:23], v[22:23], off nt
	s_nop 0
	global_load_dwordx2 v[24:25], v[24:25], off nt
	s_nop 0
	global_load_dwordx2 v[26:27], v[26:27], off nt
	s_nop 0
	global_load_dwordx2 v[28:29], v[28:29], off nt
	s_nop 0
	global_load_dwordx2 v[30:31], v[30:31], off nt
	s_nop 0
	global_load_dwordx2 v[32:33], v[32:33], off nt
	s_nop 0
	global_load_dwordx2 v[34:35], v[34:35], off nt
	s_nop 0
	global_load_dwordx2 v[36:37], v[36:37], off nt
	s_nop 0
	global_load_dwordx2 v[38:39], v[38:39], off nt
	s_nop 0
	global_load_dwordx2 v[40:41], v[40:41], off nt
	s_nop 0
	global_load_dwordx2 v[42:43], v[42:43], off nt
	s_nop 0
	global_load_dwordx2 v[44:45], v[44:45], off nt
	s_nop 0
	global_load_dwordx2 v[46:47], v[46:47], off nt
	s_nop 0
	global_load_dwordx2 v[48:49], v[48:49], off nt
	v_lshl_add_u64 v[18:19], v[10:11], 0, s[14:15]
	v_cvt_pk_bf16_f32 v80, v0, v1
	v_cvt_pk_bf16_f32 v81, v2, v3
	global_store_dwordx2 v[18:19], v[80:81], off
	v_lshl_add_u64 v[50:51], v[10:11], 0, s[0:1]
	v_lshl_add_u64 v[52:53], v[10:11], 0, s[16:17]
	v_lshl_add_u64 v[54:55], v[10:11], 0, s[18:19]
	v_lshl_add_u64 v[56:57], v[10:11], 0, s[20:21]
	v_lshl_add_u64 v[58:59], v[10:11], 0, s[22:23]
	v_lshl_add_u64 v[60:61], v[10:11], 0, s[24:25]
	v_lshl_add_u64 v[62:63], v[10:11], 0, s[26:27]
	v_lshl_add_u64 v[64:65], v[10:11], 0, s[34:35]
	v_lshl_add_u64 v[66:67], v[10:11], 0, s[36:37]
	v_lshl_add_u64 v[68:69], v[10:11], 0, s[38:39]
	v_lshl_add_u64 v[70:71], v[10:11], 0, s[40:41]
	v_lshl_add_u64 v[72:73], v[10:11], 0, s[42:43]
	v_cndmask_b32_e64 v5, 0, 1, s[64:65]
	v_lshl_add_u64 v[74:75], v[10:11], 0, s[44:45]
	v_cmp_ne_u32_e32 vcc, 1, v5
	s_waitcnt vmcnt(0)
	v_lshlrev_b32_e32 v18, 16, v16
	v_and_b32_e32 v19, 0xffff0000, v16
	v_lshlrev_b32_e32 v16, 16, v17
	v_and_b32_e32 v17, 0xffff0000, v17
	v_pk_fma_f32 v[2:3], v[12:13], v[2:3], v[16:17]
	v_pk_fma_f32 v[0:1], v[6:7], v[0:1], v[18:19]
	v_lshl_add_u64 v[76:77], v[10:11], 0, s[46:47]
	v_cvt_pk_bf16_f32 v106, v0, v1
	v_cvt_pk_bf16_f32 v107, v2, v3
	global_store_dwordx2 v[50:51], v[106:107], off
	s_mov_b64 s[64:65], 0
	s_mov_b32 s30, 0x40000
	v_lshl_add_u64 v[78:79], v[10:11], 0, s[48:49]
	s_and_b64 vcc, exec, vcc
	v_lshlrev_b32_e32 v16, 16, v20
	v_and_b32_e32 v17, 0xffff0000, v20
	v_lshlrev_b32_e32 v18, 16, v21
	v_and_b32_e32 v19, 0xffff0000, v21
	v_lshlrev_b32_e32 v20, 16, v22
	v_and_b32_e32 v21, 0xffff0000, v22
	v_lshlrev_b32_e32 v22, 16, v23
	v_and_b32_e32 v23, 0xffff0000, v23
	v_pk_fma_f32 v[2:3], v[12:13], v[2:3], v[18:19]
	v_pk_fma_f32 v[0:1], v[6:7], v[0:1], v[16:17]
	v_lshlrev_b32_e32 v80, 16, v24
	v_and_b32_e32 v81, 0xffff0000, v24
	v_lshlrev_b32_e32 v24, 16, v25
	v_and_b32_e32 v25, 0xffff0000, v25
	v_cvt_pk_bf16_f32 v16, v0, v1
	v_cvt_pk_bf16_f32 v17, v2, v3
	v_pk_fma_f32 v[2:3], v[12:13], v[2:3], v[22:23]
	v_pk_fma_f32 v[0:1], v[6:7], v[0:1], v[20:21]
	v_lshlrev_b32_e32 v82, 16, v26
	v_and_b32_e32 v83, 0xffff0000, v26
	v_lshlrev_b32_e32 v26, 16, v27
	v_and_b32_e32 v27, 0xffff0000, v27
	global_store_dwordx2 v[52:53], v[16:17], off
	v_cvt_pk_bf16_f32 v16, v0, v1
	v_cvt_pk_bf16_f32 v17, v2, v3
	v_pk_fma_f32 v[2:3], v[12:13], v[2:3], v[24:25]
	v_pk_fma_f32 v[0:1], v[6:7], v[0:1], v[80:81]
	v_lshlrev_b32_e32 v84, 16, v28
	v_and_b32_e32 v85, 0xffff0000, v28
	v_lshlrev_b32_e32 v28, 16, v29
	v_and_b32_e32 v29, 0xffff0000, v29
	global_store_dwordx2 v[54:55], v[16:17], off
	v_cvt_pk_bf16_f32 v16, v0, v1
	v_cvt_pk_bf16_f32 v17, v2, v3
	v_pk_fma_f32 v[2:3], v[12:13], v[2:3], v[26:27]
	v_pk_fma_f32 v[0:1], v[6:7], v[0:1], v[82:83]
	v_lshlrev_b32_e32 v86, 16, v30
	v_and_b32_e32 v87, 0xffff0000, v30
	v_lshlrev_b32_e32 v30, 16, v31
	v_and_b32_e32 v31, 0xffff0000, v31
	global_store_dwordx2 v[56:57], v[16:17], off
	v_cvt_pk_bf16_f32 v16, v0, v1
	v_cvt_pk_bf16_f32 v17, v2, v3
	v_pk_fma_f32 v[2:3], v[12:13], v[2:3], v[28:29]
	v_pk_fma_f32 v[0:1], v[6:7], v[0:1], v[84:85]
	v_lshlrev_b32_e32 v88, 16, v32
	v_and_b32_e32 v89, 0xffff0000, v32
	v_lshlrev_b32_e32 v32, 16, v33
	v_and_b32_e32 v33, 0xffff0000, v33
	global_store_dwordx2 v[58:59], v[16:17], off
	v_cvt_pk_bf16_f32 v16, v0, v1
	v_cvt_pk_bf16_f32 v17, v2, v3
	v_pk_fma_f32 v[2:3], v[12:13], v[2:3], v[30:31]
	v_pk_fma_f32 v[0:1], v[6:7], v[0:1], v[86:87]
	v_lshlrev_b32_e32 v90, 16, v34
	v_and_b32_e32 v91, 0xffff0000, v34
	v_lshlrev_b32_e32 v34, 16, v35
	v_and_b32_e32 v35, 0xffff0000, v35
	global_store_dwordx2 v[60:61], v[16:17], off
	v_cvt_pk_bf16_f32 v16, v0, v1
	v_cvt_pk_bf16_f32 v17, v2, v3
	v_pk_fma_f32 v[2:3], v[12:13], v[2:3], v[32:33]
	v_pk_fma_f32 v[0:1], v[6:7], v[0:1], v[88:89]
	v_lshlrev_b32_e32 v92, 16, v36
	v_and_b32_e32 v93, 0xffff0000, v36
	v_lshlrev_b32_e32 v36, 16, v37
	v_and_b32_e32 v37, 0xffff0000, v37
	global_store_dwordx2 v[62:63], v[16:17], off
	v_cvt_pk_bf16_f32 v16, v0, v1
	v_cvt_pk_bf16_f32 v17, v2, v3
	v_pk_fma_f32 v[2:3], v[12:13], v[2:3], v[34:35]
	v_pk_fma_f32 v[0:1], v[6:7], v[0:1], v[90:91]
	v_lshlrev_b32_e32 v94, 16, v38
	v_and_b32_e32 v95, 0xffff0000, v38
	v_lshlrev_b32_e32 v38, 16, v39
	v_and_b32_e32 v39, 0xffff0000, v39
	global_store_dwordx2 v[64:65], v[16:17], off
	v_cvt_pk_bf16_f32 v16, v0, v1
	v_cvt_pk_bf16_f32 v17, v2, v3
	v_pk_fma_f32 v[2:3], v[12:13], v[2:3], v[36:37]
	v_pk_fma_f32 v[0:1], v[6:7], v[0:1], v[92:93]
	v_lshlrev_b32_e32 v96, 16, v40
	v_and_b32_e32 v97, 0xffff0000, v40
	v_lshlrev_b32_e32 v40, 16, v41
	v_and_b32_e32 v41, 0xffff0000, v41
	global_store_dwordx2 v[66:67], v[16:17], off
	v_cvt_pk_bf16_f32 v16, v0, v1
	v_cvt_pk_bf16_f32 v17, v2, v3
	v_pk_fma_f32 v[2:3], v[12:13], v[2:3], v[38:39]
	v_pk_fma_f32 v[0:1], v[6:7], v[0:1], v[94:95]
	v_lshlrev_b32_e32 v98, 16, v42
	v_and_b32_e32 v99, 0xffff0000, v42
	v_lshlrev_b32_e32 v42, 16, v43
	v_and_b32_e32 v43, 0xffff0000, v43
	global_store_dwordx2 v[68:69], v[16:17], off
	v_cvt_pk_bf16_f32 v16, v0, v1
	v_cvt_pk_bf16_f32 v17, v2, v3
	v_pk_fma_f32 v[2:3], v[12:13], v[2:3], v[40:41]
	v_pk_fma_f32 v[0:1], v[6:7], v[0:1], v[96:97]
	v_lshlrev_b32_e32 v100, 16, v44
	v_and_b32_e32 v101, 0xffff0000, v44
	v_lshlrev_b32_e32 v44, 16, v45
	v_and_b32_e32 v45, 0xffff0000, v45
	global_store_dwordx2 v[70:71], v[16:17], off
	v_cvt_pk_bf16_f32 v16, v0, v1
	v_cvt_pk_bf16_f32 v17, v2, v3
	v_pk_fma_f32 v[2:3], v[12:13], v[2:3], v[42:43]
	v_pk_fma_f32 v[0:1], v[6:7], v[0:1], v[98:99]
	v_lshlrev_b32_e32 v102, 16, v46
	v_and_b32_e32 v103, 0xffff0000, v46
	v_lshlrev_b32_e32 v46, 16, v47
	v_and_b32_e32 v47, 0xffff0000, v47
	global_store_dwordx2 v[72:73], v[16:17], off
	v_cvt_pk_bf16_f32 v16, v0, v1
	v_cvt_pk_bf16_f32 v17, v2, v3
	v_pk_fma_f32 v[2:3], v[12:13], v[2:3], v[44:45]
	v_pk_fma_f32 v[0:1], v[6:7], v[0:1], v[100:101]
	v_lshlrev_b32_e32 v104, 16, v48
	v_and_b32_e32 v105, 0xffff0000, v48
	v_lshlrev_b32_e32 v48, 16, v49
	v_and_b32_e32 v49, 0xffff0000, v49
	global_store_dwordx2 v[74:75], v[16:17], off
	v_cvt_pk_bf16_f32 v16, v0, v1
	v_cvt_pk_bf16_f32 v17, v2, v3
	v_pk_fma_f32 v[2:3], v[12:13], v[2:3], v[46:47]
	v_pk_fma_f32 v[0:1], v[6:7], v[0:1], v[102:103]
	global_store_dwordx2 v[76:77], v[16:17], off
	v_cvt_pk_bf16_f32 v16, v0, v1
	v_cvt_pk_bf16_f32 v17, v2, v3
	v_pk_fma_f32 v[2:3], v[12:13], v[2:3], v[48:49]
	v_pk_fma_f32 v[0:1], v[6:7], v[0:1], v[104:105]
	global_store_dwordx2 v[78:79], v[16:17], off
	s_cbranch_vccz .LBB0_314
	v_ashrrev_i32_e32 v5, 31, v4
	v_lshlrev_b64 v[4:5], 16, v[4:5]
	v_and_b32_e32 v6, 0x3f80, v15
	v_lshl_add_u64 v[4:5], s[10:11], 0, v[4:5]
	v_lshlrev_b32_e32 v156, 2, v6
	v_lshlrev_b32_e32 v6, 6, v14
	v_lshl_add_u64 v[4:5], v[4:5], 0, v[156:157]
	v_and_b32_e32 v156, 0x1c0, v6
	v_lshlrev_b32_e32 v6, 1, v14
	v_add_u32_e32 v14, s9, v14
	v_lshl_add_u64 v[4:5], v[4:5], 0, v[156:157]
	v_and_b32_e32 v156, 48, v6
	v_cmp_lt_i32_e32 vcc, s94, v14
	v_lshl_add_u64 v[4:5], v[4:5], 0, v[156:157]
	s_or_b64 s[12:13], vcc, s[12:13]
	global_store_dwordx4 v[4:5], v[0:3], off
	s_andn2_b64 exec, exec, s[12:13]
	s_cbranch_execnz .LBB0_313

.LBB0_981:
	s_lshl_b32 s30, s0, 15
	v_lshl_add_u64 v[14:15], v[8:9], 0, s[30:31]
	global_load_dwordx2 v[14:15], v[14:15], off nt
	v_or_b32_e32 v7, s0, v6
	s_mov_b32 s3, s31
	s_mov_b32 s21, s31
	s_mov_b32 s23, s31
	s_mov_b32 s25, s31
	s_mov_b32 s27, s31
	s_mov_b32 s37, s31
	s_mov_b32 s39, s31
	s_mov_b32 s41, s31
	s_mov_b32 s43, s31
	s_mov_b32 s47, s31
	s_mov_b32 s51, s31
	s_mov_b32 s57, s31
	s_mov_b32 s63, s31
	s_mov_b32 s65, s31
	s_mov_b32 s67, s31
	s_or_b32 s2, s30, 0x8000
	s_or_b32 s20, s30, 0x10000
	s_or_b32 s22, s30, 0x18000
	s_or_b32 s24, s30, 0x20000
	s_or_b32 s26, s30, 0x28000
	s_or_b32 s36, s30, 0x30000
	s_or_b32 s38, s30, 0x38000
	s_or_b32 s40, s30, 0x40000
	s_or_b32 s42, s30, 0x48000
	s_or_b32 s46, s30, 0x50000
	s_or_b32 s50, s30, 0x58000
	s_or_b32 s56, s30, 0x60000
	s_or_b32 s62, s30, 0x68000
	s_or_b32 s64, s30, 0x70000
	s_or_b32 s66, s30, 0x78000
	v_lshl_or_b32 v16, v7, 7, v13
	v_ashrrev_i32_e32 v17, 31, v16
	v_lshl_add_u64 v[20:21], v[8:9], 0, s[2:3]
	v_lshl_add_u64 v[22:23], v[8:9], 0, s[20:21]
	v_lshl_add_u64 v[24:25], v[8:9], 0, s[22:23]
	v_lshl_add_u64 v[26:27], v[8:9], 0, s[24:25]
	v_lshl_add_u64 v[28:29], v[8:9], 0, s[26:27]
	v_lshl_add_u64 v[30:31], v[8:9], 0, s[36:37]
	v_lshl_add_u64 v[32:33], v[8:9], 0, s[38:39]
	v_lshl_add_u64 v[34:35], v[8:9], 0, s[40:41]
	v_lshl_add_u64 v[36:37], v[8:9], 0, s[42:43]
	v_lshl_add_u64 v[38:39], v[8:9], 0, s[46:47]
	v_lshl_add_u64 v[40:41], v[8:9], 0, s[50:51]
	v_lshl_add_u64 v[42:43], v[8:9], 0, s[56:57]
	v_lshl_add_u64 v[44:45], v[8:9], 0, s[62:63]
	v_lshl_add_u64 v[46:47], v[8:9], 0, s[64:65]
	v_lshl_add_u64 v[48:49], v[8:9], 0, s[66:67]
	global_load_dwordx2 v[20:21], v[20:21], off nt
	s_nop 0
	global_load_dwordx2 v[22:23], v[22:23], off nt
	s_nop 0
	global_load_dwordx2 v[24:25], v[24:25], off nt
	s_nop 0
	global_load_dwordx2 v[26:27], v[26:27], off nt
	s_nop 0
	global_load_dwordx2 v[28:29], v[28:29], off nt
	s_nop 0
	global_load_dwordx2 v[30:31], v[30:31], off nt
	s_nop 0
	global_load_dwordx2 v[32:33], v[32:33], off nt
	s_nop 0
	global_load_dwordx2 v[34:35], v[34:35], off nt
	s_nop 0
	global_load_dwordx2 v[36:37], v[36:37], off nt
	s_nop 0
	global_load_dwordx2 v[38:39], v[38:39], off nt
	s_nop 0
	global_load_dwordx2 v[40:41], v[40:41], off nt
	s_nop 0
	global_load_dwordx2 v[42:43], v[42:43], off nt
	s_nop 0
	global_load_dwordx2 v[44:45], v[44:45], off nt
	v_lshl_add_u64 v[16:17], v[16:17], 2, s[14:15]
	global_load_dwordx2 v[46:47], v[46:47], off nt
	s_nop 0
	global_load_dwordx2 v[48:49], v[48:49], off nt
	s_nop 0
	global_load_dword v80, v[16:17], off
	global_load_dword v82, v[16:17], off offset:512
	global_load_dword v84, v[16:17], off offset:1024
	global_load_dword v86, v[16:17], off offset:1536
	global_load_dword v88, v[16:17], off offset:2048
	global_load_dword v90, v[16:17], off offset:2560
	global_load_dword v92, v[16:17], off offset:3072
	global_load_dword v94, v[16:17], off offset:3584
	v_lshl_add_u64 v[50:51], v[10:11], 0, s[2:3]
	v_add_co_u32_e64 v16, s[2:3], s72, v16
	v_lshl_add_u64 v[18:19], v[10:11], 0, s[30:31]
	s_nop 0
	v_addc_co_u32_e64 v17, s[2:3], 0, v17, s[2:3]
	global_load_dword v96, v[16:17], off
	global_load_dword v98, v[16:17], off offset:512
	global_load_dword v100, v[16:17], off offset:1024
	global_load_dword v102, v[16:17], off offset:1536
	global_load_dword v104, v[16:17], off offset:2048
	global_load_dword v106, v[16:17], off offset:2560
	global_load_dword v108, v[16:17], off offset:3072
	s_nop 0
	global_load_dword v16, v[16:17], off offset:3584
	v_cvt_pk_bf16_f32 v110, v0, v1
	v_cvt_pk_bf16_f32 v111, v2, v3
	global_store_dwordx2 v[18:19], v[110:111], off
	v_lshl_add_u64 v[52:53], v[10:11], 0, s[20:21]
	v_lshl_add_u64 v[54:55], v[10:11], 0, s[22:23]
	v_lshl_add_u64 v[56:57], v[10:11], 0, s[24:25]
	v_lshl_add_u64 v[58:59], v[10:11], 0, s[26:27]
	v_lshl_add_u64 v[60:61], v[10:11], 0, s[36:37]
	v_lshl_add_u64 v[62:63], v[10:11], 0, s[38:39]
	v_lshl_add_u64 v[64:65], v[10:11], 0, s[40:41]
	v_lshl_add_u64 v[66:67], v[10:11], 0, s[42:43]
	v_lshl_add_u64 v[68:69], v[10:11], 0, s[46:47]
	v_lshl_add_u64 v[70:71], v[10:11], 0, s[50:51]
	v_lshl_add_u64 v[72:73], v[10:11], 0, s[56:57]
	v_cndmask_b32_e64 v5, 0, 1, s[68:69]
	v_lshl_add_u64 v[74:75], v[10:11], 0, s[62:63]
	v_cmp_ne_u32_e32 vcc, 1, v5
	v_lshl_add_u64 v[76:77], v[10:11], 0, s[64:65]
	s_mov_b32 s0, 16
	s_mov_b64 s[68:69], 0
	v_lshl_add_u64 v[78:79], v[10:11], 0, s[66:67]
	s_waitcnt vmcnt(0)
	v_lshlrev_b32_e32 v18, 16, v14
	v_and_b32_e32 v19, 0xffff0000, v14
	v_lshlrev_b32_e32 v14, 16, v15
	v_and_b32_e32 v15, 0xffff0000, v15
	s_and_b64 vcc, exec, vcc
	v_lshlrev_b32_e32 v110, 16, v20
	v_and_b32_e32 v111, 0xffff0000, v20
	v_lshlrev_b32_e32 v20, 16, v21
	v_and_b32_e32 v21, 0xffff0000, v21
	v_lshlrev_b32_e32 v112, 16, v22
	v_and_b32_e32 v113, 0xffff0000, v22
	v_lshlrev_b32_e32 v22, 16, v23
	v_pk_fma_f32 v[2:3], v[2:3], v[80:81], v[14:15] op_sel_hi:[1,0,1]
	v_pk_fma_f32 v[0:1], v[0:1], v[80:81], v[18:19] op_sel_hi:[1,0,1]
	v_and_b32_e32 v23, 0xffff0000, v23
	v_cvt_pk_bf16_f32 v14, v0, v1
	v_cvt_pk_bf16_f32 v15, v2, v3
	v_pk_fma_f32 v[2:3], v[82:83], v[2:3], v[20:21] op_sel_hi:[0,1,1]
	v_pk_fma_f32 v[0:1], v[82:83], v[0:1], v[110:111] op_sel_hi:[0,1,1]
	v_lshlrev_b32_e32 v114, 16, v24
	v_and_b32_e32 v115, 0xffff0000, v24
	v_lshlrev_b32_e32 v24, 16, v25
	v_and_b32_e32 v25, 0xffff0000, v25
	global_store_dwordx2 v[50:51], v[14:15], off
	v_cvt_pk_bf16_f32 v14, v0, v1
	v_cvt_pk_bf16_f32 v15, v2, v3
	v_pk_fma_f32 v[2:3], v[84:85], v[2:3], v[22:23] op_sel_hi:[0,1,1]
	v_pk_fma_f32 v[0:1], v[84:85], v[0:1], v[112:113] op_sel_hi:[0,1,1]
	v_lshlrev_b32_e32 v116, 16, v26
	v_and_b32_e32 v117, 0xffff0000, v26
	v_lshlrev_b32_e32 v26, 16, v27
	v_and_b32_e32 v27, 0xffff0000, v27
	global_store_dwordx2 v[52:53], v[14:15], off
	v_cvt_pk_bf16_f32 v14, v0, v1
	v_cvt_pk_bf16_f32 v15, v2, v3
	v_pk_fma_f32 v[2:3], v[86:87], v[2:3], v[24:25] op_sel_hi:[0,1,1]
	v_pk_fma_f32 v[0:1], v[86:87], v[0:1], v[114:115] op_sel_hi:[0,1,1]
	v_lshlrev_b32_e32 v118, 16, v28
	v_and_b32_e32 v119, 0xffff0000, v28
	v_lshlrev_b32_e32 v28, 16, v29
	v_and_b32_e32 v29, 0xffff0000, v29
	global_store_dwordx2 v[54:55], v[14:15], off
	v_cvt_pk_bf16_f32 v14, v0, v1
	v_cvt_pk_bf16_f32 v15, v2, v3
	v_pk_fma_f32 v[2:3], v[88:89], v[2:3], v[26:27] op_sel_hi:[0,1,1]
	v_pk_fma_f32 v[0:1], v[88:89], v[0:1], v[116:117] op_sel_hi:[0,1,1]
	v_lshlrev_b32_e32 v120, 16, v30
	v_and_b32_e32 v121, 0xffff0000, v30
	v_lshlrev_b32_e32 v30, 16, v31
	v_and_b32_e32 v31, 0xffff0000, v31
	global_store_dwordx2 v[56:57], v[14:15], off
	v_cvt_pk_bf16_f32 v14, v0, v1
	v_cvt_pk_bf16_f32 v15, v2, v3
	v_pk_fma_f32 v[2:3], v[90:91], v[2:3], v[28:29] op_sel_hi:[0,1,1]
	v_pk_fma_f32 v[0:1], v[90:91], v[0:1], v[118:119] op_sel_hi:[0,1,1]
	v_lshlrev_b32_e32 v122, 16, v32
	v_and_b32_e32 v123, 0xffff0000, v32
	v_lshlrev_b32_e32 v32, 16, v33
	v_and_b32_e32 v33, 0xffff0000, v33
	global_store_dwordx2 v[58:59], v[14:15], off
	v_cvt_pk_bf16_f32 v14, v0, v1
	v_cvt_pk_bf16_f32 v15, v2, v3
	v_pk_fma_f32 v[2:3], v[92:93], v[2:3], v[30:31] op_sel_hi:[0,1,1]
	v_pk_fma_f32 v[0:1], v[92:93], v[0:1], v[120:121] op_sel_hi:[0,1,1]
	v_lshlrev_b32_e32 v124, 16, v34
	v_and_b32_e32 v125, 0xffff0000, v34
	v_lshlrev_b32_e32 v34, 16, v35
	v_and_b32_e32 v35, 0xffff0000, v35
	global_store_dwordx2 v[60:61], v[14:15], off
	v_cvt_pk_bf16_f32 v14, v0, v1
	v_cvt_pk_bf16_f32 v15, v2, v3
	v_pk_fma_f32 v[2:3], v[94:95], v[2:3], v[32:33] op_sel_hi:[0,1,1]
	v_pk_fma_f32 v[0:1], v[94:95], v[0:1], v[122:123] op_sel_hi:[0,1,1]
	v_lshlrev_b32_e32 v126, 16, v36
	v_and_b32_e32 v127, 0xffff0000, v36
	v_lshlrev_b32_e32 v36, 16, v37
	v_and_b32_e32 v37, 0xffff0000, v37
	global_store_dwordx2 v[62:63], v[14:15], off
	v_cvt_pk_bf16_f32 v14, v0, v1
	v_cvt_pk_bf16_f32 v15, v2, v3
	v_pk_fma_f32 v[2:3], v[96:97], v[2:3], v[34:35] op_sel_hi:[0,1,1]
	v_pk_fma_f32 v[0:1], v[96:97], v[0:1], v[124:125] op_sel_hi:[0,1,1]
	v_lshlrev_b32_e32 v128, 16, v38
	v_and_b32_e32 v129, 0xffff0000, v38
	v_lshlrev_b32_e32 v38, 16, v39
	v_and_b32_e32 v39, 0xffff0000, v39
	global_store_dwordx2 v[64:65], v[14:15], off
	v_cvt_pk_bf16_f32 v14, v0, v1
	v_cvt_pk_bf16_f32 v15, v2, v3
	v_pk_fma_f32 v[2:3], v[98:99], v[2:3], v[36:37] op_sel_hi:[0,1,1]
	v_pk_fma_f32 v[0:1], v[98:99], v[0:1], v[126:127] op_sel_hi:[0,1,1]
	v_lshlrev_b32_e32 v130, 16, v40
	v_and_b32_e32 v131, 0xffff0000, v40
	v_lshlrev_b32_e32 v40, 16, v41
	v_and_b32_e32 v41, 0xffff0000, v41
	global_store_dwordx2 v[66:67], v[14:15], off
	v_cvt_pk_bf16_f32 v14, v0, v1
	v_cvt_pk_bf16_f32 v15, v2, v3
	v_pk_fma_f32 v[2:3], v[100:101], v[2:3], v[38:39] op_sel_hi:[0,1,1]
	v_pk_fma_f32 v[0:1], v[100:101], v[0:1], v[128:129] op_sel_hi:[0,1,1]
	v_lshlrev_b32_e32 v132, 16, v42
	v_and_b32_e32 v133, 0xffff0000, v42
	v_lshlrev_b32_e32 v42, 16, v43
	v_and_b32_e32 v43, 0xffff0000, v43
	global_store_dwordx2 v[68:69], v[14:15], off
	v_cvt_pk_bf16_f32 v14, v0, v1
	v_cvt_pk_bf16_f32 v15, v2, v3
	v_pk_fma_f32 v[2:3], v[102:103], v[2:3], v[40:41] op_sel_hi:[0,1,1]
	v_pk_fma_f32 v[0:1], v[102:103], v[0:1], v[130:131] op_sel_hi:[0,1,1]
	v_lshlrev_b32_e32 v134, 16, v44
	v_and_b32_e32 v135, 0xffff0000, v44
	v_lshlrev_b32_e32 v44, 16, v45
	v_and_b32_e32 v45, 0xffff0000, v45
	global_store_dwordx2 v[70:71], v[14:15], off
	v_cvt_pk_bf16_f32 v14, v0, v1
	v_cvt_pk_bf16_f32 v15, v2, v3
	v_pk_fma_f32 v[2:3], v[104:105], v[2:3], v[42:43] op_sel_hi:[0,1,1]
	v_pk_fma_f32 v[0:1], v[104:105], v[0:1], v[132:133] op_sel_hi:[0,1,1]
	v_lshlrev_b32_e32 v136, 16, v46
	v_and_b32_e32 v137, 0xffff0000, v46
	v_lshlrev_b32_e32 v46, 16, v47
	v_and_b32_e32 v47, 0xffff0000, v47
	global_store_dwordx2 v[72:73], v[14:15], off
	v_cvt_pk_bf16_f32 v14, v0, v1
	v_cvt_pk_bf16_f32 v15, v2, v3
	v_pk_fma_f32 v[2:3], v[106:107], v[2:3], v[44:45] op_sel_hi:[0,1,1]
	v_pk_fma_f32 v[0:1], v[106:107], v[0:1], v[134:135] op_sel_hi:[0,1,1]
	v_lshlrev_b32_e32 v138, 16, v48
	v_and_b32_e32 v139, 0xffff0000, v48
	v_lshlrev_b32_e32 v48, 16, v49
	v_and_b32_e32 v49, 0xffff0000, v49
	global_store_dwordx2 v[74:75], v[14:15], off
	v_cvt_pk_bf16_f32 v14, v0, v1
	v_cvt_pk_bf16_f32 v15, v2, v3
	v_pk_fma_f32 v[2:3], v[108:109], v[2:3], v[46:47] op_sel_hi:[0,1,1]
	v_pk_fma_f32 v[0:1], v[108:109], v[0:1], v[136:137] op_sel_hi:[0,1,1]
	global_store_dwordx2 v[76:77], v[14:15], off
	v_cvt_pk_bf16_f32 v14, v0, v1
	v_cvt_pk_bf16_f32 v15, v2, v3
	v_pk_fma_f32 v[2:3], v[16:17], v[2:3], v[48:49] op_sel_hi:[0,1,1]
	v_pk_fma_f32 v[0:1], v[16:17], v[0:1], v[138:139] op_sel_hi:[0,1,1]
	global_store_dwordx2 v[78:79], v[14:15], off
	s_cbranch_vccz .LBB0_981
	v_ashrrev_i32_e32 v5, 31, v4
	v_lshlrev_b64 v[4:5], 16, v[4:5]
	v_lshl_add_u64 v[4:5], s[16:17], 0, v[4:5]
	v_lshlrev_b32_e32 v156, 9, v13
	v_lshlrev_b32_e32 v6, 6, v12
	v_lshl_add_u64 v[4:5], v[4:5], 0, v[156:157]
	v_and_b32_e32 v156, 0x1c0, v6
	v_lshlrev_b32_e32 v6, 1, v12
	v_add_u32_e32 v12, s8, v12
	v_lshl_add_u64 v[4:5], v[4:5], 0, v[156:157]
	v_and_b32_e32 v156, 48, v6
	v_cmp_lt_i32_e32 vcc, s94, v12
	v_lshl_add_u64 v[4:5], v[4:5], 0, v[156:157]
	s_or_b64 s[18:19], vcc, s[18:19]
	global_store_dwordx4 v[4:5], v[0:3], off
	s_andn2_b64 exec, exec, s[18:19]
	s_cbranch_execnz .LBB0_980

.LBB0_1089:
	v_ashrrev_i32_e32 v17, 31, v16
	v_lshl_add_u64 v[0:1], v[16:17], 3, s[4:5]
	s_mov_b64 s[2:3], s[58:59]
	global_load_dwordx2 v[42:43], v[0:1], off nt
	s_load_dwordx2 s[2:3], s[2:3], 0x158
	v_lshlrev_b64 v[0:1], 11, v[16:17]
	v_add_u32_e32 v32, s15, v16
	s_waitcnt lgkmcnt(0)
	v_lshl_add_u64 v[0:1], s[2:3], 0, v[0:1]
	v_lshl_add_u64 v[0:1], v[0:1], 0, v[22:23]
	v_lshl_add_u64 v[2:3], v[0:1], 0, s[8:9]
	v_add_co_u32_e32 v0, vcc, 0xaf00000, v0
	global_load_dwordx2 v[44:45], v[2:3], off offset:512 nt
	global_load_dwordx2 v[46:47], v[2:3], off offset:1024 nt
	v_addc_co_u32_e32 v1, vcc, 0, v1, vcc
	v_cmp_gt_i32_e32 vcc, s0, v32
	global_load_dwordx2 v[48:49], v[0:1], off nt
	global_load_dwordx2 v[50:51], v[2:3], off offset:1536 nt
	v_cndmask_b32_e32 v0, v16, v32, vcc
	v_ashrrev_i32_e32 v1, 31, v0
	s_mov_b64 s[2:3], s[58:59]
	v_lshl_add_u64 v[2:3], v[0:1], 3, s[4:5]
	global_load_dwordx2 v[38:39], v[2:3], off nt
	s_load_dwordx2 s[2:3], s[2:3], 0x158
	v_lshlrev_b64 v[28:29], 11, v[0:1]
	global_load_dwordx4 v[12:15], v[20:21], off
	global_load_dwordx4 v[8:11], v[20:21], off offset:1024
	global_load_dwordx4 v[4:7], v[20:21], off offset:2048
	global_load_dwordx4 v[0:3], v[20:21], off offset:3072
	s_waitcnt lgkmcnt(0)
	v_lshl_add_u64 v[28:29], s[2:3], 0, v[28:29]
	v_lshl_add_u64 v[28:29], v[28:29], 0, v[22:23]
	v_add_co_u32_e64 v54, s[2:3], s1, v28
	v_lshl_add_u64 v[52:53], v[28:29], 0, s[8:9]
	s_nop 0
	v_addc_co_u32_e64 v55, s[2:3], 0, v29, s[2:3]
	global_load_dwordx2 v[36:37], v[54:55], off nt
	global_load_dwordx2 v[34:35], v[52:53], off offset:512 nt
	global_load_dwordx2 v[30:31], v[52:53], off offset:1024 nt
	global_load_dwordx2 v[28:29], v[52:53], off offset:1536 nt
	v_lshlrev_b64 v[52:53], 12, v[16:17]
	s_mov_b64 s[2:3], s[58:59]
	s_load_dwordx2 s[2:3], s[2:3], 0x150
	s_waitcnt lgkmcnt(0)
	v_lshl_add_u64 v[52:53], s[2:3], 0, v[52:53]
	v_lshl_add_u64 v[58:59], v[52:53], 0, v[26:27]
	s_waitcnt vmcnt(0)
	v_mov_b32_e32 v18, v43
	v_lshlrev_b64 v[54:55], s12, v[18:19]
	v_min_u32_e32 v17, 1, v54
	v_or_b32_e32 v17, v55, v17
	v_cvt_f32_u32_e32 v17, v17
	v_cvt_f32_u32_e32 v18, v42
	v_ldexp_f32 v17, v17, s13
	v_mul_f32_e32 v17, 0x43800000, v17
	v_fmac_f32_e32 v17, 0x33800000, v18
	v_fmamk_f32 v17, v17, 0x3a800000, v40
	v_rsq_f32_e32 v18, v17
	v_lshlrev_b32_e32 v42, 16, v44
	v_and_b32_e32 v43, 0xffff0000, v44
	v_lshlrev_b32_e32 v54, 16, v48
	v_and_b32_e32 v55, 0xffff0000, v48
	v_lshlrev_b32_e32 v48, 16, v49
	v_and_b32_e32 v49, 0xffff0000, v49
	v_lshlrev_b32_e32 v44, 16, v45
	v_and_b32_e32 v45, 0xffff0000, v45
	v_lshlrev_b32_e32 v52, 16, v46
	v_and_b32_e32 v53, 0xffff0000, v46
	v_lshlrev_b32_e32 v46, 16, v47
	v_and_b32_e32 v47, 0xffff0000, v47
	v_lshlrev_b32_e32 v56, 16, v50
	v_and_b32_e32 v57, 0xffff0000, v50
	v_lshlrev_b32_e32 v50, 16, v51
	v_and_b32_e32 v51, 0xffff0000, v51
	v_pk_mul_f32 v[54:55], v[18:19], v[54:55] op_sel_hi:[0,1]
	v_pk_mul_f32 v[48:49], v[18:19], v[48:49] op_sel_hi:[0,1]
	v_pk_mul_f32 v[60:61], v[18:19], v[42:43] op_sel_hi:[0,1]
	v_pk_mul_f32 v[62:63], v[18:19], v[44:45] op_sel_hi:[0,1]
	v_pk_mul_f32 v[64:65], v[18:19], v[52:53] op_sel_hi:[0,1]
	v_pk_mul_f32 v[52:53], v[18:19], v[46:47] op_sel_hi:[0,1]
	v_pk_mul_f32 v[66:67], v[18:19], v[56:57] op_sel_hi:[0,1]
	v_pk_mul_f32 v[56:57], v[18:19], v[50:51] op_sel_hi:[0,1]
	v_pk_mul_f32 v[44:45], v[14:15], v[48:49]
	v_pk_mul_f32 v[42:43], v[12:13], v[54:55]
	v_pk_mul_f32 v[48:49], v[10:11], v[62:63]
	v_pk_mul_f32 v[46:47], v[8:9], v[60:61]
	v_pk_mul_f32 v[52:53], v[6:7], v[52:53]
	v_pk_mul_f32 v[50:51], v[4:5], v[64:65]
	v_pk_mul_f32 v[56:57], v[2:3], v[56:57]
	v_pk_mul_f32 v[54:55], v[0:1], v[66:67]
	global_store_dwordx4 v[58:59], v[42:45], off nt
	global_store_dwordx4 v[58:59], v[46:49], off offset:1024 nt
	global_store_dwordx4 v[58:59], v[50:53], off offset:2048 nt
	global_store_dwordx4 v[58:59], v[54:57], off offset:3072 nt
	s_and_saveexec_b64 s[2:3], vcc
	s_cbranch_execz .LBB0_1088
	v_cvt_f32_u32_e32 v39, v39
	v_cvt_f32_u32_e32 v38, v38
	s_mov_b64 s[16:17], s[58:59]
	s_load_dwordx2 s[16:17], s[16:17], 0x150
	v_pk_mul_f32 v[38:39], v[38:39], s[10:11]
	v_ashrrev_i32_e32 v33, 31, v32
	v_add_f32_e32 v17, v38, v39
	v_fmamk_f32 v17, v17, 0x3a800000, v40
	v_rsq_f32_e32 v18, v17
	v_lshlrev_b64 v[32:33], 12, v[32:33]
	v_lshlrev_b32_e32 v38, 16, v36
	v_and_b32_e32 v39, 0xffff0000, v36
	v_lshlrev_b32_e32 v36, 16, v37
	v_and_b32_e32 v37, 0xffff0000, v37
	s_waitcnt lgkmcnt(0)
	v_lshl_add_u64 v[32:33], s[16:17], 0, v[32:33]
	v_mov_b32_e32 v25, v19
	v_pk_mul_f32 v[38:39], v[18:19], v[38:39] op_sel_hi:[0,1]
	v_pk_mul_f32 v[36:37], v[18:19], v[36:37] op_sel_hi:[0,1]
	v_lshl_add_u64 v[32:33], v[32:33], 0, v[24:25]
	v_pk_mul_f32 v[14:15], v[14:15], v[36:37]
	v_pk_mul_f32 v[12:13], v[12:13], v[38:39]
	global_store_dwordx4 v[32:33], v[12:15], off nt
	s_nop 1
	v_lshlrev_b32_e32 v12, 16, v34
	v_and_b32_e32 v13, 0xffff0000, v34
	v_lshlrev_b32_e32 v14, 16, v35
	v_and_b32_e32 v15, 0xffff0000, v35
	v_pk_mul_f32 v[12:13], v[18:19], v[12:13] op_sel_hi:[0,1]
	v_pk_mul_f32 v[14:15], v[18:19], v[14:15] op_sel_hi:[0,1]
	v_pk_mul_f32 v[10:11], v[10:11], v[14:15]
	v_pk_mul_f32 v[8:9], v[8:9], v[12:13]
	global_store_dwordx4 v[32:33], v[8:11], off offset:1024 nt
	s_nop 1
	v_lshlrev_b32_e32 v8, 16, v30
	v_and_b32_e32 v9, 0xffff0000, v30
	v_lshlrev_b32_e32 v10, 16, v31
	v_and_b32_e32 v11, 0xffff0000, v31
	v_pk_mul_f32 v[8:9], v[18:19], v[8:9] op_sel_hi:[0,1]
	v_pk_mul_f32 v[10:11], v[18:19], v[10:11] op_sel_hi:[0,1]
	v_pk_mul_f32 v[6:7], v[6:7], v[10:11]
	v_pk_mul_f32 v[4:5], v[4:5], v[8:9]
	global_store_dwordx4 v[32:33], v[4:7], off offset:2048 nt
	s_nop 1
	v_lshlrev_b32_e32 v4, 16, v28
	v_and_b32_e32 v5, 0xffff0000, v28
	v_lshlrev_b32_e32 v6, 16, v29
	v_and_b32_e32 v7, 0xffff0000, v29
	v_pk_mul_f32 v[4:5], v[18:19], v[4:5] op_sel_hi:[0,1]
	v_pk_mul_f32 v[6:7], v[18:19], v[6:7] op_sel_hi:[0,1]
	v_pk_mul_f32 v[2:3], v[2:3], v[6:7]
	v_pk_mul_f32 v[0:1], v[0:1], v[4:5]
	global_store_dwordx4 v[32:33], v[0:3], off offset:3072 nt
	s_branch .LBB0_1088
